# v23 + per-row rstd loads of use_rs tiles issued at K-loop exit (before the epilogue alignment barrier and kind resolution), waited for at the epilogue head
# speedup vs baseline: 1.0178x; 1.0178x over previous
;     __device__ __forceinline__ void operator()(const f32x4 (&acc)[2][2][4][2], const Unit& u, int wr, int wc, int fr, int fq) const {
;     ...
;         const int row0 = u.pm * BM + wr * 64 + fr;
;     ...
;             for (int ai = 0; ai < 2; ++ai)
; #pragma unroll
;                 for (int m = 0; m < 4; ++m) {
;                     const size_t roff = (size_t)(row0 + ai * HALF + m * 16) * ld + col0;
;                     const float rr = use_rs ? rsp[row0 + ai * HALF + m * 16] : 1.f;
.Lk_loop_done:
	s_cmp_eq_u32 s75, 1
	s_cbranch_scc1 .Lepi_rs_early
	s_cmp_eq_u32 s75, 15
	s_cbranch_scc0 .Lepi_rs_early_done
.Lepi_rs_early:
	v_lshl_add_u32 v190, s25, 8, v160
	v_ashrrev_i32_e32 v191, 31, v190
	v_lshl_add_u64 v[190:191], v[190:191], 2, s[22:23]
	global_load_dword v182, v[190:191], off
	global_load_dword v183, v[190:191], off offset:64
	global_load_dword v184, v[190:191], off offset:128
	global_load_dword v185, v[190:191], off offset:192
	global_load_dword v186, v[190:191], off offset:512
	global_load_dword v187, v[190:191], off offset:576
	global_load_dword v188, v[190:191], off offset:640
	global_load_dword v189, v[190:191], off offset:704

;     __device__ __forceinline__ void operator()(const f32x4 (&acc)[2][2][4][2], const Unit& u, int wr, int wc, int fr, int fq) const {
;     ...
;         const int row0 = u.pm * BM + wr * 64 + fr;
;         const int col0 = colt + wc * 32 + 8 * fq;
;         bf16_t* base = (bf16_t*)(ws + ob); const bf16_t* aux1 = (const bf16_t*)(ws + WS_R1); const bf16_t* aux2 = (const bf16_t*)(ws + WS_R2);
;         const float* rsp = (const float*)(ws + oRS);
;         if (k == EK_PAIRMUL || k == EK_SWIGLU) {
; #pragma unroll
;             for (int ai = 0; ai < 2; ++ai)
; #pragma unroll
;                 for (int m = 0; m < 4; ++m) {
;                     bf16_t* rowp = base + (size_t)(row0 + ai * HALF + m * 16) * ld + col0;
;                     const float rr = use_rs ? rsp[row0 + ai * HALF + m * 16] : 1.f;
;     ...
;                     const float rr = use_rs ? rsp[row0 + ai * HALF + m * 16] : 1.f;
.LBB0_714:
	s_add_u32 s40, s82, s8
	v_lshl_add_u32 v140, s25, 8, v160
	v_add_u32_e32 v142, s31, v168
	s_addc_u32 s41, s83, s9
	s_add_i32 s8, s36, -1
	s_cmp_lt_u32 s8, 2
	v_ashrrev_i32_e32 v143, 31, v142
	s_mov_b64 s[8:9], -1
	v_ashrrev_i32_e32 v141, 31, v140
	s_cselect_b64 s[30:31], -1, 0
	s_cmp_eq_u32 s75, 1
	s_cbranch_scc1 .Lepi_rs_load
	s_cmp_eq_u32 s75, 15
	s_cbranch_scc1 .Lepi_rs_load
	v_mov_b32_e32 v182, 1.0
	v_mov_b32_e32 v183, 1.0
	v_mov_b32_e32 v184, 1.0
	v_mov_b32_e32 v185, 1.0
	v_mov_b32_e32 v186, 1.0
	v_mov_b32_e32 v187, 1.0
	v_mov_b32_e32 v188, 1.0
	v_mov_b32_e32 v189, 1.0
	s_branch .Lepi_rs_done
.Lepi_rs_load:
	s_waitcnt vmcnt(0)
.Lepi_rs_done:
	s_cmp_eq_u32 s36, 3
	s_cbranch_scc1 .Lepi_sig_fast
	s_cmp_eq_u32 s36, 2
	s_cbranch_scc1 .Lepi_swiglu_fast
	s_cmp_eq_u32 s36, 1
	s_cbranch_scc1 .Lepi_pair_fast
	s_cmp_eq_u32 s36, 4
	s_cbranch_scc1 .Lepi_gate_fast
	s_cmp_eq_u32 s36, 5
	s_cbranch_scc1 .Lepi_comb_fast
	s_cmp_eq_u32 s36, 0
	s_cbranch_scc1 .Lepi_plain_fast
	s_and_b64 vcc, exec, s[30:31]
	s_cbranch_vccnz .LBB0_717
	s_cmp_lt_i32 s75, 15
	s_cbranch_scc1 .LBB0_720
	s_cmp_eq_u32 s75, 15
	s_cselect_b64 s[8:9], -1, 0
	s_cbranch_execz .LBB0_721
	s_branch .LBB0_722
